# prompt-chain q loads: two 16-byte loads per lane and row tile plus an in-register 4x4 transpose across the four 16-lane rows (v_permlane16_swap / v_permlane32_swap) instead of four uncoalesced 8-byte
# speedup vs baseline: 1.0363x; 1.0241x over previous
.LBB0_874:
	s_or_b64 exec, exec, s[12:13]
	s_ashr_i32 s69, s68, 31
	s_lshl_b64 s[10:11], s[68:69], 15
	v_and_b32_e32 v1, 63, v150
	s_add_u32 s10, s78, s10
	s_addc_u32 s11, s79, s11
	v_lshlrev_b32_e32 v148, 4, v1
	v_lshl_add_u64 v[160:161], s[10:11], 0, v[148:149]
	flat_load_dwordx4 v[8:11], v[160:161]
	v_ashrrev_i32_e32 v2, 6, v150
	s_movk_i32 s9, 0x600
	v_and_b32_e32 v156, 0xffffffc0, v150
	v_bfe_u32 v3, v150, 4, 2
	v_mul_lo_u32 v0, v2, s9
	v_and_b32_e32 v154, 15, v150
	v_add_u32_e32 v4, s20, v156
	v_add_u32_e32 v14, s80, v0
	v_lshl_add_u32 v5, v154, 11, v4
	v_lshlrev_b32_e32 v153, 2, v3
	s_lshl_b32 s90, s8, 11
	s_add_i32 s8, 0, 0x20800
	v_lshlrev_b32_e32 v13, 2, v156
	v_ashrrev_i32_e32 v12, 7, v150
	v_or_b32_e32 v5, v5, v153
	v_lshl_add_u32 v157, v1, 2, v14
	v_add_u32_e32 v18, s8, v13
	v_cmp_gt_u32_e64 s[8:9], 16, v1
	v_lshlrev_b32_e32 v1, 2, v154
	v_lshlrev_b32_e32 v158, 1, v5
	v_lshrrev_b32_e32 v108, 4, v200
	v_mul_u32_u24_e32 v108, 24, v108
	v_add_u32_e32 v158, v158, v108
	v_lshlrev_b32_e32 v5, 12, v3
	v_add3_u32 v216, s82, v13, v1
	v_lshlrev_b32_e32 v217, 5, v3
	v_lshlrev_b32_e32 v13, 4, v12
	v_lshlrev_b32_e32 v3, 3, v3
	v_add_u32_e32 v219, v18, v1
	v_or_b32_e32 v24, v13, v154
	v_add_u32_e32 v223, v14, v1
	v_or_b32_e32 v1, 4, v3
	v_cmp_gt_i32_e64 s[16:17], v1, v24
	v_or_b32_e32 v1, 5, v3
	v_cmp_gt_i32_e64 s[20:21], v1, v24
	v_or_b32_e32 v1, 2, v3
	v_cmp_gt_i32_e64 s[22:23], v1, v24
	v_or_b32_e32 v1, 6, v3
	v_cmp_gt_i32_e64 s[24:25], v1, v24
	v_or_b32_e32 v1, 3, v3
	v_cmp_gt_i32_e64 s[26:27], v1, v24
	v_or_b32_e32 v1, 7, v3
	v_cmp_gt_i32_e64 s[28:29], v1, v24
	v_or_b32_e32 v1, 32, v3
	v_cmp_gt_i32_e64 s[30:31], v1, v24
	v_or_b32_e32 v1, 36, v3
	v_cmp_gt_i32_e64 s[34:35], v1, v24
	v_or_b32_e32 v1, 33, v3
	s_movk_i32 s12, 0xc0
	v_cmp_gt_i32_e64 s[36:37], v1, v24
	v_or_b32_e32 v1, 37, v3
	v_cmp_gt_i32_e32 vcc, s12, v150
	s_lshl_b32 s12, s19, 1
	v_cmp_gt_i32_e64 s[38:39], v1, v24
	v_or_b32_e32 v1, 34, v3
	v_or_b32_e32 v4, v4, v154
	s_add_u32 s12, s4, s12
	v_cmp_gt_i32_e64 s[40:41], v1, v24
	v_or_b32_e32 v1, 38, v3
	v_and_b32_e32 v15, 1, v2
	v_add_lshl_u32 v4, v4, v5, 3
	v_or3_b32 v5, s19, v5, v154
	v_and_b32_e32 v16, 48, v150
	v_lshlrev_b32_e32 v19, 14, v2
	v_add_u32_e32 v20, 0, v148
	v_lshl_or_b32 v2, s68, 11, v154
	s_addc_u32 s13, s5, 0
	v_lshlrev_b32_e32 v148, 1, v154
	s_lshl_b32 s14, s18, 3
	v_cmp_gt_i32_e64 s[42:43], v1, v24
	v_or_b32_e32 v1, 35, v3
	v_sub_u32_e32 v0, 0, v15
	v_lshlrev_b32_e32 v6, 3, v5
	v_add_u32_e32 v17, s82, v16
	v_mov_b32_e32 v5, v149
	v_mov_b32_e32 v7, v149
	v_add_u32_e32 v218, v14, v217
	s_movk_i32 s10, 0xd0
	v_add_u32_e32 v221, v2, v13
	v_lshlrev_b32_e32 v21, 12, v12
	v_lshlrev_b32_e32 v22, 11, v15
	v_lshlrev_b32_e32 v23, 6, v12
	v_add_u32_e32 v2, -1, v15
	v_or_b32_e32 v224, v153, v13
	v_sub_u32_e32 v25, 0, v16
	v_lshl_add_u64 v[12:13], s[12:13], 0, v[148:149]
	s_add_u32 s70, s76, s14
	v_cmp_gt_i32_e64 s[44:45], v1, v24
	v_or_b32_e32 v1, 39, v3
	v_lshlrev_b32_e32 v148, 6, v15
	v_mov_b32_e32 v136, 0
	s_mov_b32 s91, 0
	v_mov_b32_e32 v159, v149
	v_cmp_gt_i32_e64 s[10:11], s10, v150
	v_cndmask_b32_e64 v220, 14, 18, vcc
	v_lshl_add_u32 v222, v24, 2, v14
	v_cmp_eq_u32_e64 s[12:13], 0, v154
	s_addc_u32 s71, s77, 0
	v_lshl_add_u64 v[162:163], s[58:59], 0, v[4:5]
	v_lshl_add_u64 v[164:165], s[56:57], 0, v[6:7]
	v_add_u32_e32 v225, v18, v16
	v_add3_u32 v226, v20, v22, v21
	v_cmp_gt_i32_e64 s[14:15], v3, v24
	v_cmp_lt_i32_e64 s[18:19], v3, v24
	v_cmp_gt_i32_e64 s[46:47], v1, v24
	v_lshl_add_u32 v227, v224, 2, v14
	v_or_b32_e32 v228, 3, v224
	v_mov_b32_e32 v1, v0
	v_mov_b32_e32 v4, v0
	v_mov_b32_e32 v3, v0
	v_mov_b32_e32 v5, v2
	v_mov_b32_e32 v6, v2
	v_mov_b32_e32 v7, v2
	v_lshl_add_u64 v[166:167], v[12:13], 0, v[148:149]
	v_add_u32_e32 v229, v17, v23
	v_add_u32_e32 v230, v218, v25
	v_add_u32_e32 v231, v20, v19
	v_mov_b32_e32 v60, 0
	v_mov_b32_e32 v61, v136
	v_mov_b32_e32 v62, v136
	v_mov_b32_e32 v63, v136
	v_mov_b32_e32 v64, 0
	v_mov_b32_e32 v65, v136
	v_mov_b32_e32 v66, v136
	v_mov_b32_e32 v67, v136
	v_mov_b32_e32 v68, 0
	v_mov_b32_e32 v69, v136
	v_mov_b32_e32 v70, v136
	v_mov_b32_e32 v71, v136
	v_mov_b32_e32 v72, 0
	v_mov_b32_e32 v73, v136
	v_mov_b32_e32 v74, v136
	v_mov_b32_e32 v75, v136
	v_mov_b32_e32 v44, 0
	v_mov_b32_e32 v45, v136
	v_mov_b32_e32 v46, v136
	v_mov_b32_e32 v47, v136
	v_mov_b32_e32 v48, 0
	v_mov_b32_e32 v49, v136
	v_mov_b32_e32 v50, v136
	v_mov_b32_e32 v51, v136
	v_mov_b32_e32 v52, 0
	v_mov_b32_e32 v53, v136
	v_mov_b32_e32 v54, v136
	v_mov_b32_e32 v55, v136
	v_mov_b32_e32 v56, 0
	v_mov_b32_e32 v57, v136
	v_mov_b32_e32 v58, v136
	v_mov_b32_e32 v59, v136
	v_mov_b32_e32 v28, 0
	v_mov_b32_e32 v29, v136
	v_mov_b32_e32 v30, v136
	v_mov_b32_e32 v31, v136
	v_mov_b32_e32 v32, 0
	v_mov_b32_e32 v33, v136
	v_mov_b32_e32 v34, v136
	v_mov_b32_e32 v35, v136
	v_mov_b32_e32 v36, 0
	v_mov_b32_e32 v37, v136
	v_mov_b32_e32 v38, v136
	v_mov_b32_e32 v39, v136
	v_mov_b32_e32 v40, 0
	v_mov_b32_e32 v41, v136
	v_mov_b32_e32 v42, v136
	v_mov_b32_e32 v43, v136
	v_mov_b32_e32 v12, 0
	v_mov_b32_e32 v13, v136
	v_mov_b32_e32 v14, v136
	v_mov_b32_e32 v15, v136
	v_mov_b32_e32 v16, 0
	v_mov_b32_e32 v17, v136
	v_mov_b32_e32 v18, v136
	v_mov_b32_e32 v19, v136
	v_mov_b32_e32 v24, 0
	v_mov_b32_e32 v25, v136
	v_mov_b32_e32 v26, v136
	v_mov_b32_e32 v27, v136
	v_mov_b32_e32 v20, 0
	v_mov_b32_e32 v21, v136
	v_mov_b32_e32 v22, v136
	v_mov_b32_e32 v23, v136
	s_branch .LBB0_876

.LBB0_876:
	s_lshl_b32 s93, s91, 6
	s_add_i32 s92, s93, s90
	s_mov_b32 s72, s92
	s_ashr_i32 s73, s72, 31
	s_lshl_b64 s[74:75], s[72:73], 12
	s_add_u32 s74, s0, s74
	s_waitcnt vmcnt(0) lgkmcnt(0)
	v_mov_b64_e32 v[140:141], v[10:11]
	s_addc_u32 s75, s1, s75
	v_mov_b64_e32 v[138:139], v[8:9]
	v_lshl_add_u64 v[8:9], s[74:75], 0, v[158:159]
	s_mov_b32 s74, 0x10000
	v_add_co_u32_e32 v10, vcc, s74, v8
	s_ashr_i32 s72, s72, 2
	s_nop 0
	v_addc_co_u32_e32 v11, vcc, 0, v9, vcc
	v_add_co_u32_e32 v76, vcc, s81, v8
	s_ashr_i32 s73, s72, 31
	s_nop 0
	v_addc_co_u32_e32 v77, vcc, 0, v9, vcc
	s_mov_b32 s74, 0x30000
	s_lshl_b64 s[72:73], s[72:73], 14
	v_add_co_u32_e32 v78, vcc, s74, v8
	s_mov_b32 s64, s91
	s_nop 0
	v_addc_co_u32_e32 v79, vcc, 0, v9, vcc
	flat_load_dwordx4 v[142:145], v[8:9]
	flat_load_dwordx4 v[132:135], v[8:9] offset:16
	flat_load_dwordx4 v[128:131], v[10:11]
	flat_load_dwordx4 v[124:127], v[10:11] offset:16
	flat_load_dwordx4 v[120:123], v[76:77]
	flat_load_dwordx4 v[116:119], v[76:77] offset:16
	flat_load_dwordx4 v[112:115], v[78:79]
	flat_load_dwordx4 v[108:111], v[78:79] offset:16
	v_lshl_add_u64 v[8:9], v[162:163], 0, s[72:73]
	v_add_co_u32_e32 v78, vcc, s83, v8
	v_lshl_add_u64 v[10:11], v[164:165], 0, s[72:73]
	s_nop 0
	v_addc_co_u32_e32 v79, vcc, 0, v9, vcc
	v_add_co_u32_e32 v80, vcc, s83, v10
	s_add_i32 s91, s91, 1
	s_nop 0
	v_addc_co_u32_e32 v81, vcc, 0, v11, vcc
	flat_load_dwordx2 v[104:105], v[8:9]
	flat_load_dwordx2 v[92:93], v[8:9] offset:128
	flat_load_dwordx2 v[84:85], v[8:9] offset:256
	flat_load_dwordx2 v[76:77], v[8:9] offset:384
	flat_load_dwordx2 v[106:107], v[78:79]
	flat_load_dwordx2 v[94:95], v[78:79] offset:128
	flat_load_dwordx2 v[86:87], v[78:79] offset:256
	s_nop 0
	flat_load_dwordx2 v[78:79], v[78:79] offset:384
	s_nop 0
	flat_load_dwordx2 v[194:195], v[10:11]
	flat_load_dwordx2 v[186:187], v[10:11] offset:128
	flat_load_dwordx2 v[192:193], v[10:11] offset:256
	flat_load_dwordx2 v[184:185], v[10:11] offset:384
	flat_load_dwordx2 v[196:197], v[80:81]
	flat_load_dwordx2 v[188:189], v[80:81] offset:128
	flat_load_dwordx2 v[198:199], v[80:81] offset:256
	flat_load_dwordx2 v[190:191], v[80:81] offset:384
	v_add_co_u32_e32 v80, vcc, s81, v8
	s_lshl_b32 s94, s91, 6
	s_nop 0
	v_addc_co_u32_e32 v81, vcc, 0, v9, vcc
	v_add_co_u32_e32 v8, vcc, s84, v8
	s_cmp_lg_u32 s64, 31
	s_nop 0
	v_addc_co_u32_e32 v9, vcc, 0, v9, vcc
	v_add_co_u32_e32 v146, vcc, s81, v10
	s_cselect_b64 s[72:73], -1, 0
	s_nop 0
	v_addc_co_u32_e32 v147, vcc, 0, v11, vcc
	v_add_co_u32_e32 v10, vcc, s84, v10
	s_and_b64 s[74:75], s[72:73], exec
	s_nop 0
	v_addc_co_u32_e32 v11, vcc, 0, v11, vcc
	flat_load_dwordx2 v[100:101], v[80:81]
	flat_load_dwordx2 v[96:97], v[80:81] offset:128
	flat_load_dwordx2 v[88:89], v[80:81] offset:256
	s_nop 0
	flat_load_dwordx2 v[80:81], v[80:81] offset:384
	s_nop 0
	flat_load_dwordx2 v[102:103], v[8:9]
	flat_load_dwordx2 v[98:99], v[8:9] offset:128
	flat_load_dwordx2 v[90:91], v[8:9] offset:256
	flat_load_dwordx2 v[82:83], v[8:9] offset:384
	flat_load_dwordx2 v[178:179], v[146:147]
	flat_load_dwordx2 v[172:173], v[146:147] offset:128
	flat_load_dwordx2 v[176:177], v[146:147] offset:256
	flat_load_dwordx2 v[168:169], v[146:147] offset:384
	flat_load_dwordx2 v[180:181], v[10:11]
	flat_load_dwordx2 v[174:175], v[10:11] offset:128
	flat_load_dwordx2 v[182:183], v[10:11] offset:256
	flat_load_dwordx2 v[170:171], v[10:11] offset:384
	s_cselect_b32 s64, s94, 0x7c0
	v_lshl_add_u64 v[8:9], s[64:65], 4, v[160:161]
	flat_load_dwordx4 v[8:11], v[8:9]
	ds_bpermute_b32 v137, v155, v140
	v_max_f32_e32 v141, v136, v136
	v_max_f32_e32 v140, v140, v140
	v_max_f32_e32 v140, v141, v140
	ds_bpermute_b32 v232, v155, v138
	s_waitcnt lgkmcnt(0)
	v_max_f32_e32 v137, v137, v137
	v_max_f32_e32 v233, v141, v137
	v_sub_f32_e32 v137, v139, v233
	v_mul_f32_e32 v137, 0x3fb8aa3b, v137
	v_sub_f32_e32 v141, v136, v140
	v_exp_f32_e32 v137, v137
	v_mul_f32_e32 v141, 0x3fb8aa3b, v141
	v_add_f32_e32 v138, v138, v140
	v_exp_f32_e32 v141, v141
	v_mul_f32_e32 v138, 0xbfb8aa3b, v138
	v_exp_f32_e32 v138, v138
	v_mul_f32_e32 v137, 0x3d3504f3, v137
	ds_write2st64_b32 v157, v139, v140 offset1:1
	ds_write2st64_b32 v157, v137, v141 offset0:2 offset1:3
	ds_write_b32 v157, v138 offset:1024
	s_waitcnt lgkmcnt(0)
	ds_read_b128 v[138:141], v225
	ds_read_b128 v[234:237], v225 offset:64
	s_waitcnt vmcnt(0)
	v_permlane16_swap_b32_e32 v142, v144
	v_permlane16_swap_b32_e32 v132, v134
	v_permlane16_swap_b32_e32 v143, v145
	v_permlane16_swap_b32_e32 v133, v135
	v_permlane16_swap_b32_e32 v128, v130
	v_permlane16_swap_b32_e32 v124, v126
	v_permlane16_swap_b32_e32 v129, v131
	v_permlane16_swap_b32_e32 v125, v127
	v_permlane16_swap_b32_e32 v120, v122
	v_permlane16_swap_b32_e32 v116, v118
	v_permlane16_swap_b32_e32 v121, v123
	v_permlane16_swap_b32_e32 v117, v119
	v_permlane16_swap_b32_e32 v112, v114
	v_permlane16_swap_b32_e32 v108, v110
	v_permlane16_swap_b32_e32 v113, v115
	v_permlane16_swap_b32_e32 v109, v111
	v_permlane32_swap_b32_e32 v142, v132
	v_permlane32_swap_b32_e32 v144, v134
	v_permlane32_swap_b32_e32 v143, v133
	v_permlane32_swap_b32_e32 v145, v135
	v_permlane32_swap_b32_e32 v128, v124
	v_permlane32_swap_b32_e32 v130, v126
	v_permlane32_swap_b32_e32 v129, v125
	v_permlane32_swap_b32_e32 v131, v127
	v_permlane32_swap_b32_e32 v120, v116
	v_permlane32_swap_b32_e32 v122, v118
	v_permlane32_swap_b32_e32 v121, v117
	v_permlane32_swap_b32_e32 v123, v119
	v_permlane32_swap_b32_e32 v112, v108
	v_permlane32_swap_b32_e32 v114, v110
	v_permlane32_swap_b32_e32 v113, v109
	v_permlane32_swap_b32_e32 v115, v111
	s_nop 1
	v_and_b32_e32 v146, 0xffff0000, v142
	v_lshlrev_b32_e32 v137, 16, v142
	v_and_b32_e32 v148, 0xffff0000, v143
	s_waitcnt lgkmcnt(1)
	v_mul_f32_e32 v139, v139, v146
	v_lshlrev_b32_e32 v147, 16, v143
	v_and_b32_e32 v239, 0xffff0000, v144
	v_fmac_f32_e32 v139, v138, v137
	v_mul_f32_e32 v137, v141, v148
	v_lshlrev_b32_e32 v238, 16, v144
	v_fmac_f32_e32 v137, v140, v147
	s_waitcnt lgkmcnt(0)
	v_mul_f32_e32 v138, v235, v239
	v_and_b32_e32 v241, 0xffff0000, v145
	v_add_f32_e32 v137, v139, v137
	v_fmac_f32_e32 v138, v234, v238
	v_lshlrev_b32_e32 v240, 16, v145
	v_add_f32_e32 v137, v137, v138
	v_mul_f32_e32 v138, v237, v241
	v_fmac_f32_e32 v138, v236, v240
	v_add_f32_e32 v137, v138, v137
	v_cvt_pk_bf16_f32 v138, v60, v61
	v_cvt_pk_bf16_f32 v139, v62, v63
	v_cvt_pk_bf16_f32 v140, v44, v45
	v_cvt_pk_bf16_f32 v141, v46, v47
	v_cvt_pk_bf16_f32 v234, v64, v65
	v_cvt_pk_bf16_f32 v235, v66, v67
	v_cvt_pk_bf16_f32 v236, v48, v49
	v_cvt_pk_bf16_f32 v237, v50, v51
	v_cvt_pk_bf16_f32 v238, v68, v69
	v_cvt_pk_bf16_f32 v239, v70, v71
	v_cvt_pk_bf16_f32 v240, v52, v53
	v_cvt_pk_bf16_f32 v241, v54, v55
	v_cvt_pk_bf16_f32 v242, v72, v73
	v_cvt_pk_bf16_f32 v243, v74, v75
	v_cvt_pk_bf16_f32 v244, v56, v57
	v_cvt_pk_bf16_f32 v245, v58, v59
	s_nop 0
	v_mfma_f32_16x16x32_bf16 v[138:141], v[142:145], v[138:141], 0
	ds_read_b128 v[246:249], v225 offset:192
	v_and_b32_e32 v147, 0xffff0000, v132
	v_lshlrev_b32_e32 v146, 16, v132
	v_mfma_f32_16x16x32_bf16 v[234:237], v[142:145], v[234:237], 0
	v_and_b32_e32 v250, 0xffff0000, v133
	v_lshlrev_b32_e32 v148, 16, v133
	v_and_b32_e32 v252, 0xffff0000, v134
	v_mfma_f32_16x16x32_bf16 v[238:241], v[142:145], v[238:241], 0
	v_lshlrev_b32_e32 v251, 16, v134
	v_and_b32_e32 v254, 0xffff0000, v135
	v_lshlrev_b32_e32 v253, 16, v135
	v_mfma_f32_16x16x32_bf16 v[142:145], v[142:145], v[242:245], 0
	ds_read_b128 v[242:245], v225 offset:128
	v_add_f32_e32 v137, 0, v137
	s_waitcnt lgkmcnt(0)
	v_mul_f32_e32 v147, v243, v147
	v_fmac_f32_e32 v147, v242, v146
	v_mul_f32_e32 v146, v245, v250
	v_fmac_f32_e32 v146, v244, v148
	v_add_f32_e32 v146, v147, v146
	v_mul_f32_e32 v147, v247, v252
	v_fmac_f32_e32 v147, v246, v251
	v_add_f32_e32 v146, v146, v147
	v_mul_f32_e32 v147, v249, v254
	v_fmac_f32_e32 v147, v248, v253
	v_add_f32_e32 v146, v147, v146
	v_add_f32_e32 v137, v137, v146
	ds_bpermute_b32 v146, v209, v137
	v_cvt_pk_bf16_f32 v242, v28, v29
	v_cvt_pk_bf16_f32 v243, v30, v31
	v_cvt_pk_bf16_f32 v244, v12, v13
	v_cvt_pk_bf16_f32 v245, v14, v15
	s_nop 0
	v_mfma_f32_16x16x32_bf16 v[138:141], v[132:135], v[242:245], v[138:141]
	v_cvt_pk_bf16_f32 v242, v32, v33
	v_cvt_pk_bf16_f32 v243, v34, v35
	v_cvt_pk_bf16_f32 v244, v16, v17
	v_cvt_pk_bf16_f32 v245, v18, v19
	s_nop 0
	v_mfma_f32_16x16x32_bf16 v[234:237], v[132:135], v[242:245], v[234:237]
	v_cvt_pk_bf16_f32 v242, v36, v37
	v_cvt_pk_bf16_f32 v243, v38, v39
	v_cvt_pk_bf16_f32 v244, v24, v25
	v_cvt_pk_bf16_f32 v245, v26, v27
	s_nop 0
	v_mfma_f32_16x16x32_bf16 v[238:241], v[132:135], v[242:245], v[238:241]
	v_cvt_pk_bf16_f32 v242, v40, v41
	v_cvt_pk_bf16_f32 v243, v42, v43
	v_cvt_pk_bf16_f32 v244, v20, v21
	v_cvt_pk_bf16_f32 v245, v22, v23
	s_nop 0
	v_mfma_f32_16x16x32_bf16 v[142:145], v[132:135], v[242:245], v[142:145]
	s_waitcnt lgkmcnt(0)
	v_add_f32_e32 v132, v137, v146
	ds_bpermute_b32 v133, v210, v132
	ds_write_b128 v231, v[138:141]
	ds_write_b128 v231, v[234:237] offset:1024
	s_nop 0
	ds_write_b128 v231, v[238:241] offset:2048
	s_nop 0
	ds_write_b128 v231, v[142:145] offset:3072
	s_and_saveexec_b64 s[74:75], s[8:9]
	s_cbranch_execz .LBB0_878
	s_waitcnt lgkmcnt(4)
	v_add_f32_e32 v132, v132, v133
	ds_write_b32 v216, v132
